# filter_gen (F3): W1/W2 weights register-resident across the t loop
# baseline (speedup 1.0000x reference)
; DI void filter_gen(const Inputs& in, int l, unsigned char* ws, LAS unsigned char* lds, int vcu, int G, int wave, int tid) {
;     ...
;     for (int it = wgi * 8 + wave; it < 4096 + 2048; it += nwg * 8) {
;         const int g = it >= 4096, t = g ? it - 4096 : it, L = g ? 2048 : 4096, FRS = g ? FRS1 : FRS0;
;         bf16_t* FR = (bf16_t*)(ws + (g ? WS_FR1 : WS_FR0)); bf16_t* FRO = (bf16_t*)(ws + (g ? WS_FRO1 : WS_FRO0));
;         const float tl = (float)t / (float)(L - 1);
;         const float w = 6.2831853071795864769f * (float)t / (float)L;
;         float z;
;         { const int k = lane; const int fi = (k >= 17) ? k - 17 : k - 1; const float f = 1e-4f + (float)fi * ((15.0f - 1e-4f) / 15.0f);
;           z = (k == 0) ? tl : (k <= 16 ? __cosf(f * w) : -__sinf(f * w)); if (k > 32) z = 0.f; }
;         float a = Bs[lane];
; #pragma unroll 11
;         for (int k = 0; k < 33; ++k) a += __shfl(z, k) * W1s[k * 64 + lane];
;         const float h1 = __sinf(a);
;         a = Bs[64 + lane];
; #pragma unroll 16
;         for (int k = 0; k < 64; ++k) a += __shfl(h1, k) * W2s[k * 64 + lane];
;         const float h2 = __sinf(a);
;         float o[4] = {0.f, 0.f, 0.f, 0.f};
; #pragma unroll 16
;         for (int k = 0; k < 64; ++k) { const float hk = __shfl(h2, k);
; #pragma unroll
;             for (int q = 0; q < 4; ++q) o[q] += hk * W3s[k * 256 + lane + 64 * q]; }
; #pragma unroll
;         for (int q = 0; q < 4; ++q) {
;             const int cidx = 256 * chunk + lane + 64 * q, dir = cidx >> 9, c = cidx & 511;
;             const float delta = fabsf(-3.0701134573253942f + (float)c * ((-15.350567286626972f + 3.0701134573253942f) / 511.0f));
.LBB0_1631:
	s_or_b64 exec, exec, s[2:3]
	s_lshl_b32 s2, s58, 1
	s_and_b32 s2, s2, -8
	s_add_i32 s22, s2, s59
	s_cmpk_gt_i32 s22, 0x17ff
	s_waitcnt lgkmcnt(0)
	s_barrier
	s_cbranch_scc1 .LBB0_1670
	v_not_b32_e32 v0, 16
	v_cmp_lt_u32_e64 s[2:3], 16, v110
	s_lshl_b32 s8, s16, 8
	v_lshlrev_b32_e32 v2, 2, v110
	v_cndmask_b32_e64 v0, -1, v0, s[2:3]
	v_add_u32_e32 v0, v0, v110
	v_cvt_f32_i32_e32 v0, v0
	s_and_b32 s8, s8, 0x100
	v_mov_b32_e32 v1, 0x38d1b717
	v_add_u32_e32 v43, 0, v2
	v_or_b32_e32 v44, s8, v2
	v_fmamk_f32 v42, v0, 0x3f7fff90, v1
	v_add_u32_e32 v0, 0x16100, v43
	v_or_b32_e32 v45, 1, v44
	v_or_b32_e32 v46, 2, v44
	v_or_b32_e32 v47, 3, v44
	s_sub_i32 s4, s33, s16
	ds_read2st64_b32 v[0:1], v0 offset1:1
	v_cvt_f32_u32_e32 v3, v44
	v_cvt_f32_u32_e32 v4, v45
	v_cvt_f32_u32_e32 v5, v46
	v_cvt_f32_u32_e32 v6, v47
	s_lshl_b32 s9, s4, 1
	s_cmp_gt_u32 s16, 1
	s_cselect_b64 s[12:13], -1, 0
	s_add_i32 s9, s9, 6
	v_mov_b32_e32 v7, 0xc0447cbd
	s_add_i32 s8, 0, 0x12100
	v_cmp_ne_u32_e64 s[4:5], 0, v110
	v_cmp_lt_u32_e64 s[6:7], 32, v110
	s_and_b32 s23, s9, -8
	v_fmamk_f32 v48, v3, 0xbcc4df2d, v7
	v_fmamk_f32 v49, v4, 0xbcc4df2d, v7
	v_fmamk_f32 v50, v5, 0xbcc4df2d, v7
	v_fmamk_f32 v51, v6, 0xbcc4df2d, v7
	v_add_u32_e32 v52, s8, v2
	v_add_u32_e32 v3, 0x10000, v43
	ds_read2st64_b32 v[110:111], v3 offset0:0 offset1:1
	ds_read2st64_b32 v[112:113], v3 offset0:2 offset1:3
	ds_read2st64_b32 v[114:115], v3 offset0:4 offset1:5
	ds_read2st64_b32 v[116:117], v3 offset0:6 offset1:7
	ds_read2st64_b32 v[118:119], v3 offset0:8 offset1:9
	ds_read2st64_b32 v[120:121], v3 offset0:10 offset1:11
	ds_read2st64_b32 v[122:123], v3 offset0:12 offset1:13
	ds_read2st64_b32 v[124:125], v3 offset0:14 offset1:15
	ds_read2st64_b32 v[126:127], v3 offset0:16 offset1:17
	ds_read2st64_b32 v[128:129], v3 offset0:18 offset1:19
	ds_read2st64_b32 v[130:131], v3 offset0:20 offset1:21
	ds_read2st64_b32 v[132:133], v3 offset0:22 offset1:23
	ds_read2st64_b32 v[134:135], v3 offset0:24 offset1:25
	ds_read2st64_b32 v[136:137], v3 offset0:26 offset1:27
	ds_read2st64_b32 v[138:139], v3 offset0:28 offset1:29
	ds_read2st64_b32 v[140:141], v3 offset0:30 offset1:31
	ds_read_b32 v142, v3 offset:8192
	ds_read2st64_b32 v[144:145], v52 offset0:0 offset1:1
	ds_read2st64_b32 v[146:147], v52 offset0:2 offset1:3
	ds_read2st64_b32 v[148:149], v52 offset0:4 offset1:5
	ds_read2st64_b32 v[150:151], v52 offset0:6 offset1:7
	ds_read2st64_b32 v[152:153], v52 offset0:8 offset1:9
	ds_read2st64_b32 v[154:155], v52 offset0:10 offset1:11
	ds_read2st64_b32 v[156:157], v52 offset0:12 offset1:13
	ds_read2st64_b32 v[158:159], v52 offset0:14 offset1:15
	ds_read2st64_b32 v[160:161], v52 offset0:16 offset1:17
	ds_read2st64_b32 v[162:163], v52 offset0:18 offset1:19
	ds_read2st64_b32 v[164:165], v52 offset0:20 offset1:21
	ds_read2st64_b32 v[166:167], v52 offset0:22 offset1:23
	ds_read2st64_b32 v[168:169], v52 offset0:24 offset1:25
	ds_read2st64_b32 v[170:171], v52 offset0:26 offset1:27
	ds_read2st64_b32 v[172:173], v52 offset0:28 offset1:29
	ds_read2st64_b32 v[174:175], v52 offset0:30 offset1:31
	ds_read2st64_b32 v[178:179], v52 offset0:32 offset1:33
	ds_read2st64_b32 v[180:181], v52 offset0:34 offset1:35
	ds_read2st64_b32 v[182:183], v52 offset0:36 offset1:37
	ds_read2st64_b32 v[184:185], v52 offset0:38 offset1:39
	ds_read2st64_b32 v[186:187], v52 offset0:40 offset1:41
	ds_read2st64_b32 v[188:189], v52 offset0:42 offset1:43
	ds_read2st64_b32 v[190:191], v52 offset0:44 offset1:45
	ds_read2st64_b32 v[192:193], v52 offset0:46 offset1:47
	ds_read2st64_b32 v[194:195], v52 offset0:48 offset1:49
	ds_read2st64_b32 v[196:197], v52 offset0:50 offset1:51
	ds_read2st64_b32 v[198:199], v52 offset0:52 offset1:53
	ds_read2st64_b32 v[200:201], v52 offset0:54 offset1:55
	ds_read2st64_b32 v[202:203], v52 offset0:56 offset1:57
	ds_read2st64_b32 v[204:205], v52 offset0:58 offset1:59
	ds_read2st64_b32 v[88:89], v52 offset0:60 offset1:61
	ds_read2st64_b32 v[90:91], v52 offset0:62 offset1:63
	s_lshr_b32 s8, s16, 1
	s_sub_i32 s9, 7, s59
	s_cmp_eq_u32 s8, 0
	s_cselect_b32 s9, s9, s59
	s_lshl_b32 s9, s9, 1
	s_add_i32 s9, s9, 0x18000
	s_and_b32 s10, s59, 3
	s_lshl_b32 s11, s10, 6
	s_lshl_b32 s10, s10, 10
	s_add_i32 s10, s10, 0x18000
	s_and_b32 s8, s16, 1
	s_lshl_b32 s8, s8, 8
	s_add_i32 s8, s8, s11
	v_lshl_add_u32 v100, v249, 6, s9
	v_lshl_add_u32 v101, v249, 4, s10
	v_add_u32_e32 v102, s8, v249
	v_lshlrev_b32_e32 v103, 4, v249
	s_branch .LBB0_1634

; DI void filter_gen(const Inputs& in, int l, unsigned char* ws, LAS unsigned char* lds, int vcu, int G, int wave, int tid) {
;     ...
;         float a = Bs[lane];
; #pragma unroll 11
;         for (int k = 0; k < 33; ++k) a += __shfl(z, k) * W1s[k * 64 + lane];
;         const float h1 = __sinf(a);
;         a = Bs[64 + lane];
; #pragma unroll 16
;         for (int k = 0; k < 64; ++k) a += __shfl(h1, k) * W2s[k * 64 + lane];
;         const float h2 = __sinf(a);
.LBB0_1640:
	s_or_b64 exec, exec, s[10:11]
	v_cndmask_b32_e64 v2, v2, 0, s[6:7]
	s_waitcnt lgkmcnt(0)
	v_mov_b32_e32 v4, v0
	s_nop 0
	v_readlane_b32 s10, v2, 0
	v_readlane_b32 s14, v2, 1
	v_readlane_b32 s16, v2, 2
	v_readlane_b32 s20, v2, 3
	v_fmac_f32_e32 v4, s10, v110
	v_fmac_f32_e32 v4, s14, v111
	v_fmac_f32_e32 v4, s16, v112
	v_fmac_f32_e32 v4, s20, v113
	v_readlane_b32 s10, v2, 4
	v_readlane_b32 s14, v2, 5
	v_readlane_b32 s16, v2, 6
	v_readlane_b32 s20, v2, 7
	v_fmac_f32_e32 v4, s10, v114
	v_fmac_f32_e32 v4, s14, v115
	v_fmac_f32_e32 v4, s16, v116
	v_fmac_f32_e32 v4, s20, v117
	v_readlane_b32 s10, v2, 8
	v_readlane_b32 s14, v2, 9
	v_readlane_b32 s16, v2, 10
	v_readlane_b32 s20, v2, 11
	v_fmac_f32_e32 v4, s10, v118
	v_fmac_f32_e32 v4, s14, v119
	v_fmac_f32_e32 v4, s16, v120
	v_fmac_f32_e32 v4, s20, v121
	v_readlane_b32 s10, v2, 12
	v_readlane_b32 s14, v2, 13
	v_readlane_b32 s16, v2, 14
	v_readlane_b32 s20, v2, 15
	v_fmac_f32_e32 v4, s10, v122
	v_fmac_f32_e32 v4, s14, v123
	v_fmac_f32_e32 v4, s16, v124
	v_fmac_f32_e32 v4, s20, v125
	v_readlane_b32 s10, v2, 16
	v_readlane_b32 s14, v2, 17
	v_readlane_b32 s16, v2, 18
	v_readlane_b32 s20, v2, 19
	v_fmac_f32_e32 v4, s10, v126
	v_fmac_f32_e32 v4, s14, v127
	v_fmac_f32_e32 v4, s16, v128
	v_fmac_f32_e32 v4, s20, v129
	v_readlane_b32 s10, v2, 20
	v_readlane_b32 s14, v2, 21
	v_readlane_b32 s16, v2, 22
	v_readlane_b32 s20, v2, 23
	v_fmac_f32_e32 v4, s10, v130
	v_fmac_f32_e32 v4, s14, v131
	v_fmac_f32_e32 v4, s16, v132
	v_fmac_f32_e32 v4, s20, v133
	v_readlane_b32 s10, v2, 24
	v_readlane_b32 s14, v2, 25
	v_readlane_b32 s16, v2, 26
	v_readlane_b32 s20, v2, 27
	v_fmac_f32_e32 v4, s10, v134
	v_fmac_f32_e32 v4, s14, v135
	v_fmac_f32_e32 v4, s16, v136
	v_fmac_f32_e32 v4, s20, v137
	v_readlane_b32 s10, v2, 28
	v_readlane_b32 s14, v2, 29
	v_readlane_b32 s16, v2, 30
	v_readlane_b32 s20, v2, 31
	v_fmac_f32_e32 v4, s10, v138
	v_fmac_f32_e32 v4, s14, v139
	v_fmac_f32_e32 v4, s16, v140
	v_fmac_f32_e32 v4, s20, v141
	v_readlane_b32 s10, v2, 32
	s_nop 1
	v_fmac_f32_e32 v4, s10, v142
	v_mul_f32_e32 v2, 0.15915494, v4
	v_sin_f32_e32 v2, v2
	v_mov_b32_e32 v4, v1
	s_nop 0
	v_readlane_b32 s10, v2, 0
	v_readlane_b32 s14, v2, 1
	v_readlane_b32 s16, v2, 2
	v_readlane_b32 s20, v2, 3
	v_fmac_f32_e32 v4, s10, v144
	v_fmac_f32_e32 v4, s14, v145
	v_fmac_f32_e32 v4, s16, v146
	v_fmac_f32_e32 v4, s20, v147
	v_readlane_b32 s10, v2, 4
	v_readlane_b32 s14, v2, 5
	v_readlane_b32 s16, v2, 6
	v_readlane_b32 s20, v2, 7
	v_fmac_f32_e32 v4, s10, v148
	v_fmac_f32_e32 v4, s14, v149
	v_fmac_f32_e32 v4, s16, v150
	v_fmac_f32_e32 v4, s20, v151
	v_readlane_b32 s10, v2, 8
	v_readlane_b32 s14, v2, 9
	v_readlane_b32 s16, v2, 10
	v_readlane_b32 s20, v2, 11
	v_fmac_f32_e32 v4, s10, v152
	v_fmac_f32_e32 v4, s14, v153
	v_fmac_f32_e32 v4, s16, v154
	v_fmac_f32_e32 v4, s20, v155
	v_readlane_b32 s10, v2, 12
	v_readlane_b32 s14, v2, 13
	v_readlane_b32 s16, v2, 14
	v_readlane_b32 s20, v2, 15
	v_fmac_f32_e32 v4, s10, v156
	v_fmac_f32_e32 v4, s14, v157
	v_fmac_f32_e32 v4, s16, v158
	v_fmac_f32_e32 v4, s20, v159
	v_readlane_b32 s10, v2, 16
	v_readlane_b32 s14, v2, 17
	v_readlane_b32 s16, v2, 18
	v_readlane_b32 s20, v2, 19
	v_fmac_f32_e32 v4, s10, v160
	v_fmac_f32_e32 v4, s14, v161
	v_fmac_f32_e32 v4, s16, v162
	v_fmac_f32_e32 v4, s20, v163
	v_readlane_b32 s10, v2, 20
	v_readlane_b32 s14, v2, 21
	v_readlane_b32 s16, v2, 22
	v_readlane_b32 s20, v2, 23
	v_fmac_f32_e32 v4, s10, v164
	v_fmac_f32_e32 v4, s14, v165
	v_fmac_f32_e32 v4, s16, v166
	v_fmac_f32_e32 v4, s20, v167
	v_readlane_b32 s10, v2, 24
	v_readlane_b32 s14, v2, 25
	v_readlane_b32 s16, v2, 26
	v_readlane_b32 s20, v2, 27
	v_fmac_f32_e32 v4, s10, v168
	v_fmac_f32_e32 v4, s14, v169
	v_fmac_f32_e32 v4, s16, v170
	v_fmac_f32_e32 v4, s20, v171
	v_readlane_b32 s10, v2, 28
	v_readlane_b32 s14, v2, 29
	v_readlane_b32 s16, v2, 30
	v_readlane_b32 s20, v2, 31
	v_fmac_f32_e32 v4, s10, v172
	v_fmac_f32_e32 v4, s14, v173
	v_fmac_f32_e32 v4, s16, v174
	v_fmac_f32_e32 v4, s20, v175
	v_readlane_b32 s10, v2, 32
	v_readlane_b32 s14, v2, 33
	v_readlane_b32 s16, v2, 34
	v_readlane_b32 s20, v2, 35
	v_fmac_f32_e32 v4, s10, v178
	v_fmac_f32_e32 v4, s14, v179
	v_fmac_f32_e32 v4, s16, v180
	v_fmac_f32_e32 v4, s20, v181
	v_readlane_b32 s10, v2, 36
	v_readlane_b32 s14, v2, 37
	v_readlane_b32 s16, v2, 38
	v_readlane_b32 s20, v2, 39
	v_fmac_f32_e32 v4, s10, v182
	v_fmac_f32_e32 v4, s14, v183
	v_fmac_f32_e32 v4, s16, v184
	v_fmac_f32_e32 v4, s20, v185
	v_readlane_b32 s10, v2, 40
	v_readlane_b32 s14, v2, 41
	v_readlane_b32 s16, v2, 42
	v_readlane_b32 s20, v2, 43
	v_fmac_f32_e32 v4, s10, v186
	v_fmac_f32_e32 v4, s14, v187
	v_fmac_f32_e32 v4, s16, v188
	v_fmac_f32_e32 v4, s20, v189
	v_readlane_b32 s10, v2, 44
	v_readlane_b32 s14, v2, 45
	v_readlane_b32 s16, v2, 46
	v_readlane_b32 s20, v2, 47
	v_fmac_f32_e32 v4, s10, v190
	v_fmac_f32_e32 v4, s14, v191
	v_fmac_f32_e32 v4, s16, v192
	v_fmac_f32_e32 v4, s20, v193
	v_readlane_b32 s10, v2, 48
	v_readlane_b32 s14, v2, 49
	v_readlane_b32 s16, v2, 50
	v_readlane_b32 s20, v2, 51
	v_fmac_f32_e32 v4, s10, v194
	v_fmac_f32_e32 v4, s14, v195
	v_fmac_f32_e32 v4, s16, v196
	v_fmac_f32_e32 v4, s20, v197
	v_readlane_b32 s10, v2, 52
	v_readlane_b32 s14, v2, 53
	v_readlane_b32 s16, v2, 54
	v_readlane_b32 s20, v2, 55
	v_fmac_f32_e32 v4, s10, v198
	v_fmac_f32_e32 v4, s14, v199
	v_fmac_f32_e32 v4, s16, v200
	v_fmac_f32_e32 v4, s20, v201
	v_readlane_b32 s10, v2, 56
	v_readlane_b32 s14, v2, 57
	v_readlane_b32 s16, v2, 58
	v_readlane_b32 s20, v2, 59
	v_fmac_f32_e32 v4, s10, v202
	v_fmac_f32_e32 v4, s14, v203
	v_fmac_f32_e32 v4, s16, v204
	v_fmac_f32_e32 v4, s20, v205
	v_readlane_b32 s10, v2, 60
	v_readlane_b32 s14, v2, 61
	v_readlane_b32 s16, v2, 62
	v_readlane_b32 s20, v2, 63
	v_fmac_f32_e32 v4, s10, v88
	v_fmac_f32_e32 v4, s14, v89
	v_fmac_f32_e32 v4, s16, v90
	v_fmac_f32_e32 v4, s20, v91
	v_mul_f32_e32 v2, 0.15915494, v4
	v_sin_f32_e32 v54, v2
	ds_read_b128 v[56:59], v103
	ds_read_b128 v[60:63], v103 offset:1024
	ds_read_b128 v[64:67], v103 offset:2048
	ds_read_b128 v[68:71], v103 offset:3072
	ds_read_b128 v[72:75], v103 offset:4096
	ds_read_b128 v[76:79], v103 offset:5120
	ds_read_b128 v[80:83], v103 offset:6144
	ds_read_b128 v[84:87], v103 offset:7168
	ds_read_b128 v[6:9], v103 offset:8192
	ds_read_b128 v[10:13], v103 offset:9216
	ds_read_b128 v[14:17], v103 offset:10240
	ds_read_b128 v[18:21], v103 offset:11264
	ds_read_b128 v[22:25], v103 offset:12288
	ds_read_b128 v[26:29], v103 offset:13312
	ds_read_b128 v[30:33], v103 offset:14336
	ds_read_b128 v[34:37], v103 offset:15360
	v_mov_b32_e32 v4, 0
	v_mov_b32_e32 v5, 0
	v_mov_b32_e32 v2, 0
	v_mov_b32_e32 v3, 0
	s_waitcnt lgkmcnt(8)
; DI void filter_gen(const Inputs& in, int l, unsigned char* ws, LAS unsigned char* lds, int vcu, int G, int wave, int tid) {
;     ...
;         float o[4] = {0.f, 0.f, 0.f, 0.f};
; #pragma unroll 16
;         for (int k = 0; k < 64; ++k) { const float hk = __shfl(h2, k);
; #pragma unroll
;             for (int q = 0; q < 4; ++q) o[q] += hk * W3s[k * 256 + lane + 64 * q]; }
	v_readlane_b32 s10, v54, 0
	v_readlane_b32 s14, v54, 1
	v_readlane_b32 s16, v54, 2
	v_readlane_b32 s20, v54, 3
	v_pk_fma_f32 v[4:5], v[56:57], s[10:11], v[4:5] op_sel_hi:[1,0,1]
	v_pk_fma_f32 v[2:3], v[58:59], s[10:11], v[2:3] op_sel_hi:[1,0,1]
	v_pk_fma_f32 v[4:5], v[60:61], s[14:15], v[4:5] op_sel_hi:[1,0,1]
	v_pk_fma_f32 v[2:3], v[62:63], s[14:15], v[2:3] op_sel_hi:[1,0,1]
	v_pk_fma_f32 v[4:5], v[64:65], s[16:17], v[4:5] op_sel_hi:[1,0,1]
	v_pk_fma_f32 v[2:3], v[66:67], s[16:17], v[2:3] op_sel_hi:[1,0,1]
	v_pk_fma_f32 v[4:5], v[68:69], s[20:21], v[4:5] op_sel_hi:[1,0,1]
	v_pk_fma_f32 v[2:3], v[70:71], s[20:21], v[2:3] op_sel_hi:[1,0,1]
	v_readlane_b32 s10, v54, 4
	v_readlane_b32 s14, v54, 5
	v_readlane_b32 s16, v54, 6
	v_readlane_b32 s20, v54, 7
	v_pk_fma_f32 v[4:5], v[72:73], s[10:11], v[4:5] op_sel_hi:[1,0,1]
	v_pk_fma_f32 v[2:3], v[74:75], s[10:11], v[2:3] op_sel_hi:[1,0,1]
	v_pk_fma_f32 v[4:5], v[76:77], s[14:15], v[4:5] op_sel_hi:[1,0,1]
	v_pk_fma_f32 v[2:3], v[78:79], s[14:15], v[2:3] op_sel_hi:[1,0,1]
	v_pk_fma_f32 v[4:5], v[80:81], s[16:17], v[4:5] op_sel_hi:[1,0,1]
	v_pk_fma_f32 v[2:3], v[82:83], s[16:17], v[2:3] op_sel_hi:[1,0,1]
	v_pk_fma_f32 v[4:5], v[84:85], s[20:21], v[4:5] op_sel_hi:[1,0,1]
	v_pk_fma_f32 v[2:3], v[86:87], s[20:21], v[2:3] op_sel_hi:[1,0,1]
	ds_read_b128 v[56:59], v103 offset:16384
	ds_read_b128 v[60:63], v103 offset:17408
	ds_read_b128 v[64:67], v103 offset:18432
	ds_read_b128 v[68:71], v103 offset:19456
	ds_read_b128 v[72:75], v103 offset:20480
	ds_read_b128 v[76:79], v103 offset:21504
	ds_read_b128 v[80:83], v103 offset:22528
	ds_read_b128 v[84:87], v103 offset:23552
	s_waitcnt lgkmcnt(8)
	v_readlane_b32 s10, v54, 8
	v_readlane_b32 s14, v54, 9
	v_readlane_b32 s16, v54, 10
	v_readlane_b32 s20, v54, 11
	v_pk_fma_f32 v[4:5], v[6:7], s[10:11], v[4:5] op_sel_hi:[1,0,1]
	v_pk_fma_f32 v[2:3], v[8:9], s[10:11], v[2:3] op_sel_hi:[1,0,1]
	v_pk_fma_f32 v[4:5], v[10:11], s[14:15], v[4:5] op_sel_hi:[1,0,1]
	v_pk_fma_f32 v[2:3], v[12:13], s[14:15], v[2:3] op_sel_hi:[1,0,1]
	v_pk_fma_f32 v[4:5], v[14:15], s[16:17], v[4:5] op_sel_hi:[1,0,1]
	v_pk_fma_f32 v[2:3], v[16:17], s[16:17], v[2:3] op_sel_hi:[1,0,1]
	v_pk_fma_f32 v[4:5], v[18:19], s[20:21], v[4:5] op_sel_hi:[1,0,1]
	v_pk_fma_f32 v[2:3], v[20:21], s[20:21], v[2:3] op_sel_hi:[1,0,1]
	v_readlane_b32 s10, v54, 12
	v_readlane_b32 s14, v54, 13
	v_readlane_b32 s16, v54, 14
	v_readlane_b32 s20, v54, 15
	v_pk_fma_f32 v[4:5], v[22:23], s[10:11], v[4:5] op_sel_hi:[1,0,1]
	v_pk_fma_f32 v[2:3], v[24:25], s[10:11], v[2:3] op_sel_hi:[1,0,1]
	v_pk_fma_f32 v[4:5], v[26:27], s[14:15], v[4:5] op_sel_hi:[1,0,1]
	v_pk_fma_f32 v[2:3], v[28:29], s[14:15], v[2:3] op_sel_hi:[1,0,1]
	v_pk_fma_f32 v[4:5], v[30:31], s[16:17], v[4:5] op_sel_hi:[1,0,1]
	v_pk_fma_f32 v[2:3], v[32:33], s[16:17], v[2:3] op_sel_hi:[1,0,1]
	v_pk_fma_f32 v[4:5], v[34:35], s[20:21], v[4:5] op_sel_hi:[1,0,1]
	v_pk_fma_f32 v[2:3], v[36:37], s[20:21], v[2:3] op_sel_hi:[1,0,1]
	ds_read_b128 v[6:9], v103 offset:24576
	ds_read_b128 v[10:13], v103 offset:25600
	ds_read_b128 v[14:17], v103 offset:26624
	ds_read_b128 v[18:21], v103 offset:27648
	ds_read_b128 v[22:25], v103 offset:28672
	ds_read_b128 v[26:29], v103 offset:29696
	ds_read_b128 v[30:33], v103 offset:30720
	ds_read_b128 v[34:37], v103 offset:31744
	s_waitcnt lgkmcnt(8)
	v_readlane_b32 s10, v54, 16
	v_readlane_b32 s14, v54, 17
	v_readlane_b32 s16, v54, 18
	v_readlane_b32 s20, v54, 19
	v_pk_fma_f32 v[4:5], v[56:57], s[10:11], v[4:5] op_sel_hi:[1,0,1]
	v_pk_fma_f32 v[2:3], v[58:59], s[10:11], v[2:3] op_sel_hi:[1,0,1]
	v_pk_fma_f32 v[4:5], v[60:61], s[14:15], v[4:5] op_sel_hi:[1,0,1]
	v_pk_fma_f32 v[2:3], v[62:63], s[14:15], v[2:3] op_sel_hi:[1,0,1]
	v_pk_fma_f32 v[4:5], v[64:65], s[16:17], v[4:5] op_sel_hi:[1,0,1]
	v_pk_fma_f32 v[2:3], v[66:67], s[16:17], v[2:3] op_sel_hi:[1,0,1]
	v_pk_fma_f32 v[4:5], v[68:69], s[20:21], v[4:5] op_sel_hi:[1,0,1]
	v_pk_fma_f32 v[2:3], v[70:71], s[20:21], v[2:3] op_sel_hi:[1,0,1]
	v_readlane_b32 s10, v54, 20
	v_readlane_b32 s14, v54, 21
	v_readlane_b32 s16, v54, 22
	v_readlane_b32 s20, v54, 23
	v_pk_fma_f32 v[4:5], v[72:73], s[10:11], v[4:5] op_sel_hi:[1,0,1]
	v_pk_fma_f32 v[2:3], v[74:75], s[10:11], v[2:3] op_sel_hi:[1,0,1]
	v_pk_fma_f32 v[4:5], v[76:77], s[14:15], v[4:5] op_sel_hi:[1,0,1]
	v_pk_fma_f32 v[2:3], v[78:79], s[14:15], v[2:3] op_sel_hi:[1,0,1]
	v_pk_fma_f32 v[4:5], v[80:81], s[16:17], v[4:5] op_sel_hi:[1,0,1]
	v_pk_fma_f32 v[2:3], v[82:83], s[16:17], v[2:3] op_sel_hi:[1,0,1]
	v_pk_fma_f32 v[4:5], v[84:85], s[20:21], v[4:5] op_sel_hi:[1,0,1]
	v_pk_fma_f32 v[2:3], v[86:87], s[20:21], v[2:3] op_sel_hi:[1,0,1]
	ds_read_b128 v[56:59], v103 offset:32768
	ds_read_b128 v[60:63], v103 offset:33792
	ds_read_b128 v[64:67], v103 offset:34816
	ds_read_b128 v[68:71], v103 offset:35840
	ds_read_b128 v[72:75], v103 offset:36864
	ds_read_b128 v[76:79], v103 offset:37888
	ds_read_b128 v[80:83], v103 offset:38912
	ds_read_b128 v[84:87], v103 offset:39936
	s_waitcnt lgkmcnt(8)
; DI void filter_gen(const Inputs& in, int l, unsigned char* ws, LAS unsigned char* lds, int vcu, int G, int wave, int tid) {
;     ...
;         float o[4] = {0.f, 0.f, 0.f, 0.f};
; #pragma unroll 16
;         for (int k = 0; k < 64; ++k) { const float hk = __shfl(h2, k);
; #pragma unroll
;             for (int q = 0; q < 4; ++q) o[q] += hk * W3s[k * 256 + lane + 64 * q]; }
	v_readlane_b32 s10, v54, 24
	v_readlane_b32 s14, v54, 25
	v_readlane_b32 s16, v54, 26
	v_readlane_b32 s20, v54, 27
	v_pk_fma_f32 v[4:5], v[6:7], s[10:11], v[4:5] op_sel_hi:[1,0,1]
	v_pk_fma_f32 v[2:3], v[8:9], s[10:11], v[2:3] op_sel_hi:[1,0,1]
	v_pk_fma_f32 v[4:5], v[10:11], s[14:15], v[4:5] op_sel_hi:[1,0,1]
	v_pk_fma_f32 v[2:3], v[12:13], s[14:15], v[2:3] op_sel_hi:[1,0,1]
	v_pk_fma_f32 v[4:5], v[14:15], s[16:17], v[4:5] op_sel_hi:[1,0,1]
	v_pk_fma_f32 v[2:3], v[16:17], s[16:17], v[2:3] op_sel_hi:[1,0,1]
	v_pk_fma_f32 v[4:5], v[18:19], s[20:21], v[4:5] op_sel_hi:[1,0,1]
	v_pk_fma_f32 v[2:3], v[20:21], s[20:21], v[2:3] op_sel_hi:[1,0,1]
	v_readlane_b32 s10, v54, 28
	v_readlane_b32 s14, v54, 29
	v_readlane_b32 s16, v54, 30
	v_readlane_b32 s20, v54, 31
	v_pk_fma_f32 v[4:5], v[22:23], s[10:11], v[4:5] op_sel_hi:[1,0,1]
	v_pk_fma_f32 v[2:3], v[24:25], s[10:11], v[2:3] op_sel_hi:[1,0,1]
	v_pk_fma_f32 v[4:5], v[26:27], s[14:15], v[4:5] op_sel_hi:[1,0,1]
	v_pk_fma_f32 v[2:3], v[28:29], s[14:15], v[2:3] op_sel_hi:[1,0,1]
	v_pk_fma_f32 v[4:5], v[30:31], s[16:17], v[4:5] op_sel_hi:[1,0,1]
	v_pk_fma_f32 v[2:3], v[32:33], s[16:17], v[2:3] op_sel_hi:[1,0,1]
	v_pk_fma_f32 v[4:5], v[34:35], s[20:21], v[4:5] op_sel_hi:[1,0,1]
	v_pk_fma_f32 v[2:3], v[36:37], s[20:21], v[2:3] op_sel_hi:[1,0,1]
	ds_read_b128 v[6:9], v103 offset:40960
	ds_read_b128 v[10:13], v103 offset:41984
	ds_read_b128 v[14:17], v103 offset:43008
	ds_read_b128 v[18:21], v103 offset:44032
	ds_read_b128 v[22:25], v103 offset:45056
	ds_read_b128 v[26:29], v103 offset:46080
	ds_read_b128 v[30:33], v103 offset:47104
	ds_read_b128 v[34:37], v103 offset:48128
	s_waitcnt lgkmcnt(8)
	v_readlane_b32 s10, v54, 32
	v_readlane_b32 s14, v54, 33
	v_readlane_b32 s16, v54, 34
	v_readlane_b32 s20, v54, 35
	v_pk_fma_f32 v[4:5], v[56:57], s[10:11], v[4:5] op_sel_hi:[1,0,1]
	v_pk_fma_f32 v[2:3], v[58:59], s[10:11], v[2:3] op_sel_hi:[1,0,1]
	v_pk_fma_f32 v[4:5], v[60:61], s[14:15], v[4:5] op_sel_hi:[1,0,1]
	v_pk_fma_f32 v[2:3], v[62:63], s[14:15], v[2:3] op_sel_hi:[1,0,1]
	v_pk_fma_f32 v[4:5], v[64:65], s[16:17], v[4:5] op_sel_hi:[1,0,1]
	v_pk_fma_f32 v[2:3], v[66:67], s[16:17], v[2:3] op_sel_hi:[1,0,1]
	v_pk_fma_f32 v[4:5], v[68:69], s[20:21], v[4:5] op_sel_hi:[1,0,1]
	v_pk_fma_f32 v[2:3], v[70:71], s[20:21], v[2:3] op_sel_hi:[1,0,1]
	v_readlane_b32 s10, v54, 36
	v_readlane_b32 s14, v54, 37
	v_readlane_b32 s16, v54, 38
	v_readlane_b32 s20, v54, 39
	v_pk_fma_f32 v[4:5], v[72:73], s[10:11], v[4:5] op_sel_hi:[1,0,1]
	v_pk_fma_f32 v[2:3], v[74:75], s[10:11], v[2:3] op_sel_hi:[1,0,1]
	v_pk_fma_f32 v[4:5], v[76:77], s[14:15], v[4:5] op_sel_hi:[1,0,1]
	v_pk_fma_f32 v[2:3], v[78:79], s[14:15], v[2:3] op_sel_hi:[1,0,1]
	v_pk_fma_f32 v[4:5], v[80:81], s[16:17], v[4:5] op_sel_hi:[1,0,1]
	v_pk_fma_f32 v[2:3], v[82:83], s[16:17], v[2:3] op_sel_hi:[1,0,1]
	v_pk_fma_f32 v[4:5], v[84:85], s[20:21], v[4:5] op_sel_hi:[1,0,1]
	v_pk_fma_f32 v[2:3], v[86:87], s[20:21], v[2:3] op_sel_hi:[1,0,1]
	ds_read_b128 v[56:59], v103 offset:49152
	ds_read_b128 v[60:63], v103 offset:50176
	ds_read_b128 v[64:67], v103 offset:51200
	ds_read_b128 v[68:71], v103 offset:52224
	ds_read_b128 v[72:75], v103 offset:53248
	ds_read_b128 v[76:79], v103 offset:54272
	ds_read_b128 v[80:83], v103 offset:55296
	ds_read_b128 v[84:87], v103 offset:56320
	s_waitcnt lgkmcnt(8)
	v_readlane_b32 s10, v54, 40
	v_readlane_b32 s14, v54, 41
	v_readlane_b32 s16, v54, 42
	v_readlane_b32 s20, v54, 43
	v_pk_fma_f32 v[4:5], v[6:7], s[10:11], v[4:5] op_sel_hi:[1,0,1]
	v_pk_fma_f32 v[2:3], v[8:9], s[10:11], v[2:3] op_sel_hi:[1,0,1]
	v_pk_fma_f32 v[4:5], v[10:11], s[14:15], v[4:5] op_sel_hi:[1,0,1]
	v_pk_fma_f32 v[2:3], v[12:13], s[14:15], v[2:3] op_sel_hi:[1,0,1]
	v_pk_fma_f32 v[4:5], v[14:15], s[16:17], v[4:5] op_sel_hi:[1,0,1]
	v_pk_fma_f32 v[2:3], v[16:17], s[16:17], v[2:3] op_sel_hi:[1,0,1]
	v_pk_fma_f32 v[4:5], v[18:19], s[20:21], v[4:5] op_sel_hi:[1,0,1]
	v_pk_fma_f32 v[2:3], v[20:21], s[20:21], v[2:3] op_sel_hi:[1,0,1]
	v_readlane_b32 s10, v54, 44
	v_readlane_b32 s14, v54, 45
	v_readlane_b32 s16, v54, 46
	v_readlane_b32 s20, v54, 47
	v_pk_fma_f32 v[4:5], v[22:23], s[10:11], v[4:5] op_sel_hi:[1,0,1]
	v_pk_fma_f32 v[2:3], v[24:25], s[10:11], v[2:3] op_sel_hi:[1,0,1]
	v_pk_fma_f32 v[4:5], v[26:27], s[14:15], v[4:5] op_sel_hi:[1,0,1]
	v_pk_fma_f32 v[2:3], v[28:29], s[14:15], v[2:3] op_sel_hi:[1,0,1]
	v_pk_fma_f32 v[4:5], v[30:31], s[16:17], v[4:5] op_sel_hi:[1,0,1]
	v_pk_fma_f32 v[2:3], v[32:33], s[16:17], v[2:3] op_sel_hi:[1,0,1]
	v_pk_fma_f32 v[4:5], v[34:35], s[20:21], v[4:5] op_sel_hi:[1,0,1]
	v_pk_fma_f32 v[2:3], v[36:37], s[20:21], v[2:3] op_sel_hi:[1,0,1]
	ds_read_b128 v[6:9], v103 offset:57344
	ds_read_b128 v[10:13], v103 offset:58368
	ds_read_b128 v[14:17], v103 offset:59392
	ds_read_b128 v[18:21], v103 offset:60416
	ds_read_b128 v[22:25], v103 offset:61440
	ds_read_b128 v[26:29], v103 offset:62464
	ds_read_b128 v[30:33], v103 offset:63488
	ds_read_b128 v[34:37], v103 offset:64512
	s_waitcnt lgkmcnt(8)
; DI void filter_gen(const Inputs& in, int l, unsigned char* ws, LAS unsigned char* lds, int vcu, int G, int wave, int tid) {
;     ...
;         float o[4] = {0.f, 0.f, 0.f, 0.f};
; #pragma unroll 16
;         for (int k = 0; k < 64; ++k) { const float hk = __shfl(h2, k);
; #pragma unroll
;             for (int q = 0; q < 4; ++q) o[q] += hk * W3s[k * 256 + lane + 64 * q]; }
; #pragma unroll
;         for (int q = 0; q < 4; ++q) {
;             const int cidx = 256 * chunk + lane + 64 * q, dir = cidx >> 9, c = cidx & 511;
;             const float delta = fabsf(-3.0701134573253942f + (float)c * ((-15.350567286626972f + 3.0701134573253942f) / 511.0f));
;             const float val = o[q] * __expf(-tl * delta);
;             bf16_t* row = FR + (size_t)c * FRS; bf16_t* rowo = FRO + (size_t)c * FRS;
;             if (dir == 0) { row[L - t] = f2bf(val); rowo[L - t - 1] = f2bf(val); }
;             else if (t >= 1) { row[L + t] = f2bf(val); rowo[L + t - 1] = f2bf(val); }
;         }
	v_readlane_b32 s10, v54, 48
	v_readlane_b32 s14, v54, 49
	v_readlane_b32 s16, v54, 50
	v_readlane_b32 s20, v54, 51
	v_pk_fma_f32 v[4:5], v[56:57], s[10:11], v[4:5] op_sel_hi:[1,0,1]
	v_pk_fma_f32 v[2:3], v[58:59], s[10:11], v[2:3] op_sel_hi:[1,0,1]
	v_pk_fma_f32 v[4:5], v[60:61], s[14:15], v[4:5] op_sel_hi:[1,0,1]
	v_pk_fma_f32 v[2:3], v[62:63], s[14:15], v[2:3] op_sel_hi:[1,0,1]
	v_pk_fma_f32 v[4:5], v[64:65], s[16:17], v[4:5] op_sel_hi:[1,0,1]
	v_pk_fma_f32 v[2:3], v[66:67], s[16:17], v[2:3] op_sel_hi:[1,0,1]
	v_pk_fma_f32 v[4:5], v[68:69], s[20:21], v[4:5] op_sel_hi:[1,0,1]
	v_pk_fma_f32 v[2:3], v[70:71], s[20:21], v[2:3] op_sel_hi:[1,0,1]
	v_readlane_b32 s10, v54, 52
	v_readlane_b32 s14, v54, 53
	v_readlane_b32 s16, v54, 54
	v_readlane_b32 s20, v54, 55
	v_pk_fma_f32 v[4:5], v[72:73], s[10:11], v[4:5] op_sel_hi:[1,0,1]
	v_pk_fma_f32 v[2:3], v[74:75], s[10:11], v[2:3] op_sel_hi:[1,0,1]
	v_pk_fma_f32 v[4:5], v[76:77], s[14:15], v[4:5] op_sel_hi:[1,0,1]
	v_pk_fma_f32 v[2:3], v[78:79], s[14:15], v[2:3] op_sel_hi:[1,0,1]
	v_pk_fma_f32 v[4:5], v[80:81], s[16:17], v[4:5] op_sel_hi:[1,0,1]
	v_pk_fma_f32 v[2:3], v[82:83], s[16:17], v[2:3] op_sel_hi:[1,0,1]
	v_pk_fma_f32 v[4:5], v[84:85], s[20:21], v[4:5] op_sel_hi:[1,0,1]
	v_pk_fma_f32 v[2:3], v[86:87], s[20:21], v[2:3] op_sel_hi:[1,0,1]
	s_waitcnt lgkmcnt(0)
	v_readlane_b32 s10, v54, 56
	v_readlane_b32 s14, v54, 57
	v_readlane_b32 s16, v54, 58
	v_readlane_b32 s20, v54, 59
	v_pk_fma_f32 v[4:5], v[6:7], s[10:11], v[4:5] op_sel_hi:[1,0,1]
	v_pk_fma_f32 v[2:3], v[8:9], s[10:11], v[2:3] op_sel_hi:[1,0,1]
	v_pk_fma_f32 v[4:5], v[10:11], s[14:15], v[4:5] op_sel_hi:[1,0,1]
	v_pk_fma_f32 v[2:3], v[12:13], s[14:15], v[2:3] op_sel_hi:[1,0,1]
	v_pk_fma_f32 v[4:5], v[14:15], s[16:17], v[4:5] op_sel_hi:[1,0,1]
	v_pk_fma_f32 v[2:3], v[16:17], s[16:17], v[2:3] op_sel_hi:[1,0,1]
	v_pk_fma_f32 v[4:5], v[18:19], s[20:21], v[4:5] op_sel_hi:[1,0,1]
	v_pk_fma_f32 v[2:3], v[20:21], s[20:21], v[2:3] op_sel_hi:[1,0,1]
	v_readlane_b32 s10, v54, 60
	v_readlane_b32 s14, v54, 61
	v_readlane_b32 s16, v54, 62
	v_readlane_b32 s20, v54, 63
	v_pk_fma_f32 v[4:5], v[22:23], s[10:11], v[4:5] op_sel_hi:[1,0,1]
	v_pk_fma_f32 v[2:3], v[24:25], s[10:11], v[2:3] op_sel_hi:[1,0,1]
	v_pk_fma_f32 v[4:5], v[26:27], s[14:15], v[4:5] op_sel_hi:[1,0,1]
	v_pk_fma_f32 v[2:3], v[28:29], s[14:15], v[2:3] op_sel_hi:[1,0,1]
	v_pk_fma_f32 v[4:5], v[30:31], s[16:17], v[4:5] op_sel_hi:[1,0,1]
	v_pk_fma_f32 v[2:3], v[32:33], s[16:17], v[2:3] op_sel_hi:[1,0,1]
	v_pk_fma_f32 v[4:5], v[34:35], s[20:21], v[4:5] op_sel_hi:[1,0,1]
	v_pk_fma_f32 v[2:3], v[36:37], s[20:21], v[2:3] op_sel_hi:[1,0,1]
	v_mul_f32_e64 v6, |v48|, v53
	v_mul_f32_e64 v7, |v49|, v53
	v_mul_f32_e64 v8, |v50|, v53
	v_mul_f32_e64 v9, |v51|, v53
	v_mul_f32_e32 v6, 0xbfb8aa3b, v6
	v_mul_f32_e32 v7, 0xbfb8aa3b, v7
	v_mul_f32_e32 v8, 0xbfb8aa3b, v8
	v_mul_f32_e32 v9, 0xbfb8aa3b, v9
	v_exp_f32_e32 v6, v6
	v_exp_f32_e32 v7, v7
	v_exp_f32_e32 v8, v8
	v_exp_f32_e32 v9, v9
	s_sub_i32 s10, s18, s59
	s_cmp_gt_u32 s59, 3
	s_cselect_b32 s11, 1, 0
	s_sub_i32 s14, s19, s10
	s_add_i32 s14, s14, -7
	s_add_i32 s15, s19, s10
	s_and_b64 s[20:21], s[12:13], exec
	s_cselect_b32 s14, s15, s14
	s_sub_i32 s14, s14, s11
	s_lshl_b32 s14, s14, 1
	s_and_b64 s[20:21], s[8:9], exec
	s_mov_b32 s15, 0xc10000
	s_cselect_b32 s15, s15, 0x400000
	s_mov_b32 s16, 0x1e510000
	s_cselect_b32 s16, s16, 0x1dd00000
	s_movk_i32 s24, 0x2040
	s_cselect_b32 s24, 0x1040, s24
	s_cmp_eq_u32 s11, 0
	s_cselect_b32 s15, s15, s16
	s_add_u32 s16, s34, s15
	s_addc_u32 s17, s35, 0
	s_add_u32 s16, s16, s14
	s_addc_u32 s17, s17, 0
	v_mul_f32_e32 v4, v6, v4
	v_mul_f32_e32 v5, v7, v5
	v_mul_f32_e32 v2, v8, v2
	v_mul_f32_e32 v3, v9, v3
	v_cvt_pk_bf16_f32 v4, v4, v4
	v_cvt_pk_bf16_f32 v5, v5, v5
	v_cvt_pk_bf16_f32 v2, v2, v2
	v_cvt_pk_bf16_f32 v3, v3, v3
	ds_write_b16 v100, v4
	ds_write_b16 v100, v5 offset:16
	ds_write_b16 v100, v2 offset:32
	ds_write_b16 v100, v3 offset:48
	s_waitcnt lgkmcnt(0)
	s_barrier
	ds_read_b128 v[96:99], v101
	v_xor_b32_e32 v100, 0x1000, v100
	v_mul_u32_u24_e32 v104, s24, v102
	v_mov_b32_e32 v105, 0
	v_lshlrev_b32_e32 v104, 1, v104
	v_xor_b32_e32 v101, 0x1000, v101
	s_and_b64 s[20:21], s[12:13], exec
	s_cselect_b32 s15, 1, 0
	s_cmp_eq_u32 s10, 0
	s_cselect_b32 s15, s15, 0
	v_lshl_add_u64 v[104:105], s[16:17], 0, v[104:105]
	s_cmp_lg_u32 s15, 0
	s_waitcnt lgkmcnt(0)
	s_cbranch_scc1 .Lfg_special_f3
	global_store_dwordx4 v[104:105], v[96:99], off
	s_branch .LBB0_1633
